# baseline (speedup 1.0000x reference)
; __device__ __forceinline__ float bf2f(unsigned short v) { return __uint_as_float(((unsigned)v) << 16); }
; __device__ __forceinline__ void dsa_tile(const Params& p, unsigned char* smem, int tile) {
;     ...
;         unsigned char* iqs = smem + 8192;
; #pragma unroll
;         for (int i = 0; i < 4; ++i) { const int ch = tid + 512 * i, r = ch >> 7, c = ch & 127;
;             *(u32x4*)(iqs + r * 2048 + ((c ^ r) * 16)) = *(const u32x4*)(projb + (size_t)(q0 + r) * INP + C_IQ + c * 8); }
;         float* wl = (float*)(smem + 40960);
;         if (tid < 256) { const int q = tid & 15, h = tid >> 4; wl[h * 16 + q] = bf2f(projb[(size_t)(q0 + q) * INP + C_IW + h]) * 0.015625f; }
;         __syncthreads();
;         u32x4 yf[16][2];
; #pragma unroll
;         for (int h = 0; h < 16; ++h)
; #pragma unroll
;             for (int ks = 0; ks < 2; ++ks) yf[h][ks] = *(const u32x4*)(iqs + fr * 2048 + (((h * 8 + ks * 4 + fq) ^ fr) * 16));
;         u32x4 chi[2], clo[2];
; #pragma unroll
;         for (int ks = 0; ks < 2; ++ks) {
;             float c[8];
; #pragma unroll
;             for (int e = 0; e < 8; ++e) c[e] = 0.f;
; #pragma unroll
;             for (int h = 0; h < 16; ++h) { const float wh = wl[h * 16 + fr]; float f[8]; unpack8(yf[h][ks], f);
; #pragma unroll
;                 for (int e = 0; e < 8; ++e) c[e] += wh * f[e]; }
.LBB0_287:
	s_or_b64 exec, exec, s[12:13]
	v_bfe_u32 v120, v152, 4, 2
	s_movk_i32 s4, 0x44
	v_bitop3_b32 v65, v120, v153, s4 bitop3:0x36
	s_movk_i32 s4, 0x48
	v_bitop3_b32 v72, v120, v153, s4 bitop3:0x36
	s_movk_i32 s4, 0x4c
	v_bitop3_b32 v73, v120, v153, s4 bitop3:0x36
	s_movk_i32 s4, 0x50
	v_bitop3_b32 v80, v120, v153, s4 bitop3:0x36
	s_movk_i32 s4, 0x54
	v_bitop3_b32 v81, v120, v153, s4 bitop3:0x36
	s_movk_i32 s4, 0x58
	v_bitop3_b32 v88, v120, v153, s4 bitop3:0x36
	s_movk_i32 s4, 0x5c
	v_bitop3_b32 v89, v120, v153, s4 bitop3:0x36
	s_movk_i32 s4, 0x60
	v_bitop3_b32 v96, v120, v153, s4 bitop3:0x36
	s_movk_i32 s4, 0x64
	v_bitop3_b32 v97, v120, v153, s4 bitop3:0x36
	s_movk_i32 s4, 0x68
	v_bitop3_b32 v104, v120, v153, s4 bitop3:0x36
	s_movk_i32 s4, 0x6c
	v_bitop3_b32 v105, v120, v153, s4 bitop3:0x36
	s_movk_i32 s4, 0x70
	v_bitop3_b32 v112, v120, v153, s4 bitop3:0x36
	s_movk_i32 s4, 0x74
	v_bitop3_b32 v113, v120, v153, s4 bitop3:0x36
	s_movk_i32 s4, 0x78
	v_bitop3_b32 v122, v120, v153, s4 bitop3:0x36
	s_movk_i32 s4, 0x7c
	v_lshl_add_u32 v121, v153, 11, 0
	v_xor_b32_e32 v0, v120, v153
	v_bitop3_b32 v1, v120, v153, 4 bitop3:0x36
	v_bitop3_b32 v8, v120, v153, 8 bitop3:0x36
	v_bitop3_b32 v9, v120, v153, 12 bitop3:0x36
	v_bitop3_b32 v16, v120, v153, 16 bitop3:0x36
	v_bitop3_b32 v17, v120, v153, 20 bitop3:0x36
	v_bitop3_b32 v24, v120, v153, 24 bitop3:0x36
	v_bitop3_b32 v25, v120, v153, 28 bitop3:0x36
	v_bitop3_b32 v32, v120, v153, 32 bitop3:0x36
	v_bitop3_b32 v33, v120, v153, 36 bitop3:0x36
	v_bitop3_b32 v40, v120, v153, 40 bitop3:0x36
	v_bitop3_b32 v41, v120, v153, 44 bitop3:0x36
	v_bitop3_b32 v48, v120, v153, 48 bitop3:0x36
	v_bitop3_b32 v49, v120, v153, 52 bitop3:0x36
	v_bitop3_b32 v56, v120, v153, 56 bitop3:0x36
	v_bitop3_b32 v57, v120, v153, 60 bitop3:0x36
	v_bitop3_b32 v64, v120, v153, 64 bitop3:0x36
	v_bitop3_b32 v120, v120, v153, s4 bitop3:0x36
	v_lshl_add_u32 v154, v153, 2, 0
	v_lshl_add_u32 v0, v0, 4, v121
	v_lshl_add_u32 v4, v1, 4, v121
	v_lshl_add_u32 v8, v8, 4, v121
	v_lshl_add_u32 v12, v9, 4, v121
	v_lshl_add_u32 v16, v16, 4, v121
	v_lshl_add_u32 v20, v17, 4, v121
	v_lshl_add_u32 v24, v24, 4, v121
	v_lshl_add_u32 v28, v25, 4, v121
	v_lshl_add_u32 v32, v32, 4, v121
	v_lshl_add_u32 v36, v33, 4, v121
	v_lshl_add_u32 v40, v40, 4, v121
	v_lshl_add_u32 v44, v41, 4, v121
	v_lshl_add_u32 v48, v48, 4, v121
	v_lshl_add_u32 v52, v49, 4, v121
	v_lshl_add_u32 v56, v56, 4, v121
	v_lshl_add_u32 v60, v57, 4, v121
	v_lshl_add_u32 v64, v64, 4, v121
	v_lshl_add_u32 v68, v65, 4, v121
	v_lshl_add_u32 v72, v72, 4, v121
	v_lshl_add_u32 v76, v73, 4, v121
	v_lshl_add_u32 v80, v80, 4, v121
	v_lshl_add_u32 v84, v81, 4, v121
	v_lshl_add_u32 v88, v88, 4, v121
	v_lshl_add_u32 v92, v89, 4, v121
	v_lshl_add_u32 v96, v96, 4, v121
	v_lshl_add_u32 v100, v97, 4, v121
	v_lshl_add_u32 v104, v104, 4, v121
	v_lshl_add_u32 v108, v105, 4, v121
	v_lshl_add_u32 v112, v112, 4, v121
	v_lshl_add_u32 v116, v113, 4, v121
	v_lshl_add_u32 v122, v122, 4, v121
	v_lshl_add_u32 v124, v120, 4, v121
	v_add_u32_e32 v155, 0xa000, v154
	s_waitcnt lgkmcnt(0)
	s_barrier
	ds_read_b128 v[0:3], v0 offset:8192
	ds_read_b128 v[4:7], v4 offset:8192
	ds_read_b128 v[8:11], v8 offset:8192
	ds_read_b128 v[12:15], v12 offset:8192
	ds_read_b128 v[16:19], v16 offset:8192
	ds_read_b128 v[20:23], v20 offset:8192
	ds_read_b128 v[24:27], v24 offset:8192
	ds_read_b128 v[28:31], v28 offset:8192
	ds_read_b128 v[32:35], v32 offset:8192
	ds_read_b128 v[36:39], v36 offset:8192
	ds_read_b128 v[40:43], v40 offset:8192
	ds_read_b128 v[44:47], v44 offset:8192
	ds_read_b128 v[48:51], v48 offset:8192
	ds_read_b128 v[52:55], v52 offset:8192
	ds_read_b128 v[56:59], v56 offset:8192
	ds_read_b128 v[60:63], v60 offset:8192
	ds_read_b128 v[64:67], v64 offset:8192
	ds_read_b128 v[68:71], v68 offset:8192
	ds_read_b128 v[72:75], v72 offset:8192
	ds_read_b128 v[76:79], v76 offset:8192
	ds_read_b128 v[80:83], v80 offset:8192
	ds_read_b128 v[84:87], v84 offset:8192
	ds_read_b128 v[88:91], v88 offset:8192
	ds_read_b128 v[92:95], v92 offset:8192
	ds_read_b128 v[96:99], v96 offset:8192
	ds_read_b128 v[100:103], v100 offset:8192
	ds_read_b128 v[104:107], v104 offset:8192
	ds_read_b128 v[108:111], v108 offset:8192
	ds_read_b128 v[112:115], v112 offset:8192
	ds_read_b128 v[116:119], v116 offset:8192
	ds_read_b128 v[120:123], v122 offset:8192
	ds_read_b128 v[124:127], v124 offset:8192
	ds_read2_b32 v[128:129], v155 offset1:16
	s_waitcnt lgkmcnt(14)
	v_lshlrev_b32_e32 v130, 16, v0
	v_and_b32_e32 v131, 0xffff0000, v0
	v_lshlrev_b32_e32 v132, 16, v1
	v_and_b32_e32 v133, 0xffff0000, v1
	v_lshlrev_b32_e32 v134, 16, v2
	v_and_b32_e32 v135, 0xffff0000, v2
	v_lshlrev_b32_e32 v136, 16, v3
	v_and_b32_e32 v137, 0xffff0000, v3
	s_waitcnt lgkmcnt(0)
	v_fma_f32 v138, v128, v130, 0
	v_fma_f32 v139, v128, v131, 0
	v_fma_f32 v132, v128, v132, 0
	v_fma_f32 v133, v128, v133, 0
	v_fma_f32 v134, v128, v134, 0
	v_fma_f32 v135, v128, v135, 0
	v_fma_f32 v136, v128, v136, 0
	v_fma_f32 v137, v128, v137, 0
	v_lshlrev_b32_e32 v128, 16, v8
	v_and_b32_e32 v130, 0xffff0000, v8
	v_lshlrev_b32_e32 v131, 16, v9
	v_and_b32_e32 v140, 0xffff0000, v9
	v_lshlrev_b32_e32 v141, 16, v10
	v_and_b32_e32 v142, 0xffff0000, v10
	v_lshlrev_b32_e32 v143, 16, v11
	v_and_b32_e32 v144, 0xffff0000, v11
	v_fmac_f32_e32 v138, v129, v128
	v_fmac_f32_e32 v139, v129, v130
	v_fmac_f32_e32 v132, v129, v131
	v_fmac_f32_e32 v133, v129, v140
	v_fmac_f32_e32 v134, v129, v141
	v_fmac_f32_e32 v135, v129, v142
	v_fmac_f32_e32 v136, v129, v143
	v_fmac_f32_e32 v137, v129, v144
	ds_read2_b32 v[128:129], v155 offset0:32 offset1:48
	v_lshlrev_b32_e32 v130, 16, v16
	v_and_b32_e32 v131, 0xffff0000, v16
	v_lshlrev_b32_e32 v140, 16, v17
	v_and_b32_e32 v141, 0xffff0000, v17
	v_lshlrev_b32_e32 v142, 16, v18
	v_and_b32_e32 v143, 0xffff0000, v18
	v_lshlrev_b32_e32 v144, 16, v19
	v_and_b32_e32 v145, 0xffff0000, v19
	s_waitcnt lgkmcnt(0)
; __device__ __forceinline__ void dsa_tile(const Params& p, unsigned char* smem, int tile) {
;     ...
;             for (int h = 0; h < 16; ++h) { const float wh = wl[h * 16 + fr]; float f[8]; unpack8(yf[h][ks], f);
; #pragma unroll
;                 for (int e = 0; e < 8; ++e) c[e] += wh * f[e]; }
	v_fmac_f32_e32 v138, v128, v130
	v_fmac_f32_e32 v139, v128, v131
	v_fmac_f32_e32 v132, v128, v140
	v_fmac_f32_e32 v133, v128, v141
	v_fmac_f32_e32 v134, v128, v142
	v_fmac_f32_e32 v135, v128, v143
	v_fmac_f32_e32 v136, v128, v144
	v_fmac_f32_e32 v137, v128, v145
	v_lshlrev_b32_e32 v128, 16, v24
	v_and_b32_e32 v130, 0xffff0000, v24
	v_lshlrev_b32_e32 v131, 16, v25
	v_and_b32_e32 v140, 0xffff0000, v25
	v_lshlrev_b32_e32 v141, 16, v26
	v_and_b32_e32 v142, 0xffff0000, v26
	v_lshlrev_b32_e32 v143, 16, v27
	v_and_b32_e32 v144, 0xffff0000, v27
	v_fmac_f32_e32 v138, v129, v128
	v_fmac_f32_e32 v139, v129, v130
	v_fmac_f32_e32 v132, v129, v131
	v_fmac_f32_e32 v133, v129, v140
	v_fmac_f32_e32 v134, v129, v141
	v_fmac_f32_e32 v135, v129, v142
	v_fmac_f32_e32 v136, v129, v143
	v_fmac_f32_e32 v137, v129, v144
	ds_read2_b32 v[128:129], v155 offset0:64 offset1:80
	v_lshlrev_b32_e32 v130, 16, v32
	v_and_b32_e32 v131, 0xffff0000, v32
	v_lshlrev_b32_e32 v140, 16, v33
	v_and_b32_e32 v141, 0xffff0000, v33
	v_lshlrev_b32_e32 v142, 16, v34
	v_and_b32_e32 v143, 0xffff0000, v34
	v_lshlrev_b32_e32 v144, 16, v35
	v_and_b32_e32 v145, 0xffff0000, v35
	s_waitcnt lgkmcnt(0)
	v_fmac_f32_e32 v138, v128, v130
	v_fmac_f32_e32 v139, v128, v131
	v_fmac_f32_e32 v132, v128, v140
	v_fmac_f32_e32 v133, v128, v141
	v_fmac_f32_e32 v134, v128, v142
	v_fmac_f32_e32 v135, v128, v143
	v_fmac_f32_e32 v136, v128, v144
	v_fmac_f32_e32 v137, v128, v145
	v_lshlrev_b32_e32 v128, 16, v40
	v_and_b32_e32 v130, 0xffff0000, v40
	v_lshlrev_b32_e32 v131, 16, v41
	v_and_b32_e32 v140, 0xffff0000, v41
	v_lshlrev_b32_e32 v141, 16, v42
	v_and_b32_e32 v142, 0xffff0000, v42
	v_lshlrev_b32_e32 v143, 16, v43
	v_and_b32_e32 v144, 0xffff0000, v43
	v_fmac_f32_e32 v138, v129, v128
	v_fmac_f32_e32 v139, v129, v130
	v_fmac_f32_e32 v132, v129, v131
	v_fmac_f32_e32 v133, v129, v140
	v_fmac_f32_e32 v134, v129, v141
	v_fmac_f32_e32 v135, v129, v142
	v_fmac_f32_e32 v136, v129, v143
	v_fmac_f32_e32 v137, v129, v144
	ds_read2_b32 v[128:129], v155 offset0:96 offset1:112
	v_lshlrev_b32_e32 v130, 16, v48
	v_and_b32_e32 v131, 0xffff0000, v48
	v_lshlrev_b32_e32 v140, 16, v49
	v_and_b32_e32 v141, 0xffff0000, v49
	v_lshlrev_b32_e32 v142, 16, v50
	v_and_b32_e32 v143, 0xffff0000, v50
	v_lshlrev_b32_e32 v144, 16, v51
	v_and_b32_e32 v145, 0xffff0000, v51
	s_waitcnt lgkmcnt(0)
	v_fmac_f32_e32 v138, v128, v130
	v_fmac_f32_e32 v139, v128, v131
	v_fmac_f32_e32 v132, v128, v140
	v_fmac_f32_e32 v133, v128, v141
	v_fmac_f32_e32 v134, v128, v142
	v_fmac_f32_e32 v135, v128, v143
	v_fmac_f32_e32 v136, v128, v144
	v_fmac_f32_e32 v137, v128, v145
	v_lshlrev_b32_e32 v128, 16, v56
	v_and_b32_e32 v130, 0xffff0000, v56
	v_lshlrev_b32_e32 v131, 16, v57
	v_and_b32_e32 v140, 0xffff0000, v57
	v_lshlrev_b32_e32 v141, 16, v58
	v_and_b32_e32 v142, 0xffff0000, v58
	v_lshlrev_b32_e32 v143, 16, v59
	v_and_b32_e32 v144, 0xffff0000, v59
	v_fmac_f32_e32 v138, v129, v128
	v_fmac_f32_e32 v139, v129, v130
	v_fmac_f32_e32 v132, v129, v131
	v_fmac_f32_e32 v133, v129, v140
	v_fmac_f32_e32 v134, v129, v141
	v_fmac_f32_e32 v135, v129, v142
	v_fmac_f32_e32 v136, v129, v143
	v_fmac_f32_e32 v137, v129, v144
	ds_read2_b32 v[128:129], v155 offset0:128 offset1:144
	v_lshlrev_b32_e32 v130, 16, v64
	v_and_b32_e32 v131, 0xffff0000, v64
	v_lshlrev_b32_e32 v140, 16, v65
	v_and_b32_e32 v141, 0xffff0000, v65
	v_lshlrev_b32_e32 v142, 16, v66
	v_and_b32_e32 v143, 0xffff0000, v66
	v_lshlrev_b32_e32 v144, 16, v67
	v_and_b32_e32 v145, 0xffff0000, v67
	s_waitcnt lgkmcnt(0)
	v_fmac_f32_e32 v138, v128, v130
	v_fmac_f32_e32 v139, v128, v131
	v_fmac_f32_e32 v132, v128, v140
	v_fmac_f32_e32 v133, v128, v141
	v_fmac_f32_e32 v134, v128, v142
	v_fmac_f32_e32 v135, v128, v143
	v_fmac_f32_e32 v136, v128, v144
	v_fmac_f32_e32 v137, v128, v145
	v_lshlrev_b32_e32 v128, 16, v72
	v_and_b32_e32 v130, 0xffff0000, v72
	v_lshlrev_b32_e32 v131, 16, v73
	v_and_b32_e32 v140, 0xffff0000, v73
	v_lshlrev_b32_e32 v141, 16, v74
	v_and_b32_e32 v142, 0xffff0000, v74
	v_lshlrev_b32_e32 v143, 16, v75
	v_and_b32_e32 v144, 0xffff0000, v75
	v_fmac_f32_e32 v138, v129, v128
	v_fmac_f32_e32 v139, v129, v130
	v_fmac_f32_e32 v132, v129, v131
	v_fmac_f32_e32 v133, v129, v140
	v_fmac_f32_e32 v134, v129, v141
	v_fmac_f32_e32 v135, v129, v142
	v_fmac_f32_e32 v136, v129, v143
	v_fmac_f32_e32 v137, v129, v144
	ds_read2_b32 v[128:129], v155 offset0:160 offset1:176
	v_lshlrev_b32_e32 v130, 16, v80
	v_and_b32_e32 v131, 0xffff0000, v80
	v_lshlrev_b32_e32 v140, 16, v81
	v_and_b32_e32 v141, 0xffff0000, v81
	v_lshlrev_b32_e32 v142, 16, v82
	v_and_b32_e32 v143, 0xffff0000, v82
	v_lshlrev_b32_e32 v144, 16, v83
	v_and_b32_e32 v145, 0xffff0000, v83
	s_waitcnt lgkmcnt(0)
	v_fmac_f32_e32 v138, v128, v130
	v_fmac_f32_e32 v139, v128, v131
	v_fmac_f32_e32 v132, v128, v140
	v_fmac_f32_e32 v133, v128, v141
	v_fmac_f32_e32 v134, v128, v142
	v_fmac_f32_e32 v135, v128, v143
	v_fmac_f32_e32 v136, v128, v144
	v_fmac_f32_e32 v137, v128, v145
	v_lshlrev_b32_e32 v128, 16, v88
	v_and_b32_e32 v130, 0xffff0000, v88
	v_lshlrev_b32_e32 v131, 16, v89
	v_and_b32_e32 v140, 0xffff0000, v89
	v_lshlrev_b32_e32 v141, 16, v90
	v_and_b32_e32 v142, 0xffff0000, v90
	v_lshlrev_b32_e32 v143, 16, v91
	v_and_b32_e32 v144, 0xffff0000, v91
	v_fmac_f32_e32 v138, v129, v128
	v_fmac_f32_e32 v139, v129, v130
	v_fmac_f32_e32 v132, v129, v131
	v_fmac_f32_e32 v133, v129, v140
	v_fmac_f32_e32 v134, v129, v141
	v_fmac_f32_e32 v135, v129, v142
	v_fmac_f32_e32 v136, v129, v143
	v_fmac_f32_e32 v137, v129, v144
	ds_read2_b32 v[128:129], v155 offset0:192 offset1:208
	v_lshlrev_b32_e32 v130, 16, v96
	v_and_b32_e32 v131, 0xffff0000, v96
	v_lshlrev_b32_e32 v140, 16, v97
	v_and_b32_e32 v141, 0xffff0000, v97
	v_lshlrev_b32_e32 v142, 16, v98
	v_and_b32_e32 v143, 0xffff0000, v98
	v_lshlrev_b32_e32 v144, 16, v99
	v_and_b32_e32 v145, 0xffff0000, v99
	s_waitcnt lgkmcnt(0)
; __device__ __forceinline__ void dsa_tile(const Params& p, unsigned char* smem, int tile) {
;     ...
;             for (int h = 0; h < 16; ++h) { const float wh = wl[h * 16 + fr]; float f[8]; unpack8(yf[h][ks], f);
; #pragma unroll
;                 for (int e = 0; e < 8; ++e) c[e] += wh * f[e]; }
;             chi[ks] = pack8(c);
;             float fh[8]; unpack8(chi[ks], fh);
; #pragma unroll
;             for (int e = 0; e < 8; ++e) c[e] -= fh[e];
;             clo[ks] = pack8(c);
	v_fmac_f32_e32 v138, v128, v130
	v_fmac_f32_e32 v139, v128, v131
	v_fmac_f32_e32 v132, v128, v140
	v_fmac_f32_e32 v133, v128, v141
	v_fmac_f32_e32 v134, v128, v142
	v_fmac_f32_e32 v135, v128, v143
	v_fmac_f32_e32 v136, v128, v144
	v_fmac_f32_e32 v137, v128, v145
	v_lshlrev_b32_e32 v128, 16, v104
	v_and_b32_e32 v130, 0xffff0000, v104
	v_lshlrev_b32_e32 v131, 16, v105
	v_and_b32_e32 v140, 0xffff0000, v105
	v_lshlrev_b32_e32 v141, 16, v106
	v_and_b32_e32 v142, 0xffff0000, v106
	v_lshlrev_b32_e32 v143, 16, v107
	v_and_b32_e32 v144, 0xffff0000, v107
	v_fmac_f32_e32 v138, v129, v128
	v_fmac_f32_e32 v139, v129, v130
	v_fmac_f32_e32 v132, v129, v131
	v_fmac_f32_e32 v133, v129, v140
	v_fmac_f32_e32 v134, v129, v141
	v_fmac_f32_e32 v135, v129, v142
	v_fmac_f32_e32 v136, v129, v143
	v_fmac_f32_e32 v137, v129, v144
	ds_read2_b32 v[128:129], v155 offset0:224 offset1:240
	v_lshlrev_b32_e32 v130, 16, v112
	v_and_b32_e32 v131, 0xffff0000, v112
	v_lshlrev_b32_e32 v140, 16, v113
	v_and_b32_e32 v141, 0xffff0000, v113
	v_lshlrev_b32_e32 v142, 16, v114
	v_and_b32_e32 v143, 0xffff0000, v114
	v_lshlrev_b32_e32 v144, 16, v115
	v_and_b32_e32 v145, 0xffff0000, v115
	s_waitcnt lgkmcnt(0)
	v_fmac_f32_e32 v138, v128, v130
	v_fmac_f32_e32 v139, v128, v131
	v_fmac_f32_e32 v132, v128, v140
	v_fmac_f32_e32 v133, v128, v141
	v_fmac_f32_e32 v134, v128, v142
	v_fmac_f32_e32 v135, v128, v143
	v_fmac_f32_e32 v136, v128, v144
	v_fmac_f32_e32 v137, v128, v145
	v_lshlrev_b32_e32 v128, 16, v120
	v_and_b32_e32 v130, 0xffff0000, v120
	v_lshlrev_b32_e32 v131, 16, v121
	v_and_b32_e32 v140, 0xffff0000, v121
	v_lshlrev_b32_e32 v141, 16, v122
	v_and_b32_e32 v142, 0xffff0000, v122
	v_lshlrev_b32_e32 v143, 16, v123
	v_and_b32_e32 v144, 0xffff0000, v123
	v_fmac_f32_e32 v138, v129, v128
	v_fmac_f32_e32 v139, v129, v130
	v_fmac_f32_e32 v132, v129, v131
	v_fmac_f32_e32 v133, v129, v140
	v_fmac_f32_e32 v134, v129, v141
	v_fmac_f32_e32 v135, v129, v142
	v_fmac_f32_e32 v136, v129, v143
	v_fmac_f32_e32 v137, v129, v144
	v_cvt_pk_bf16_f32 v128, v138, v139
	v_cvt_pk_bf16_f32 v129, v132, v133
	v_cvt_pk_bf16_f32 v130, v134, v135
	v_cvt_pk_bf16_f32 v131, v136, v137
	v_and_b32_e32 v148, 0xffff0000, v13
	v_and_b32_e32 v143, 0xffff0000, v129
	v_lshlrev_b32_e32 v144, 16, v130
	v_and_b32_e32 v145, 0xffff0000, v130
	v_lshlrev_b32_e32 v146, 16, v131
	v_and_b32_e32 v147, 0xffff0000, v131
	v_lshlrev_b32_e32 v140, 16, v128
	v_and_b32_e32 v141, 0xffff0000, v128
	v_lshlrev_b32_e32 v142, 16, v129
	v_sub_f32_e32 v133, v133, v143
	v_sub_f32_e32 v134, v134, v144
	v_sub_f32_e32 v135, v135, v145
	v_sub_f32_e32 v136, v136, v146
	v_sub_f32_e32 v137, v137, v147
	v_sub_f32_e32 v138, v138, v140
	v_sub_f32_e32 v139, v139, v141
	v_sub_f32_e32 v140, v132, v142
	v_cvt_pk_bf16_f32 v132, v138, v139
	v_cvt_pk_bf16_f32 v133, v140, v133
	v_cvt_pk_bf16_f32 v134, v134, v135
	v_cvt_pk_bf16_f32 v135, v136, v137
	ds_read2_b32 v[136:137], v155 offset1:16
	v_lshlrev_b32_e32 v138, 16, v4
	v_and_b32_e32 v139, 0xffff0000, v4
	v_lshlrev_b32_e32 v140, 16, v5
	v_and_b32_e32 v141, 0xffff0000, v5
	v_lshlrev_b32_e32 v142, 16, v6
	v_and_b32_e32 v143, 0xffff0000, v6
	v_lshlrev_b32_e32 v144, 16, v7
	v_and_b32_e32 v145, 0xffff0000, v7
	s_waitcnt lgkmcnt(0)
	v_fma_f32 v146, v136, v138, 0
	v_fma_f32 v147, v136, v139, 0
	v_fma_f32 v140, v136, v140, 0
	v_fma_f32 v141, v136, v141, 0
	v_fma_f32 v142, v136, v142, 0
	v_fma_f32 v143, v136, v143, 0
	v_fma_f32 v144, v136, v144, 0
	v_fma_f32 v145, v136, v145, 0
	v_lshlrev_b32_e32 v136, 16, v12
	v_and_b32_e32 v138, 0xffff0000, v12
	v_lshlrev_b32_e32 v139, 16, v13
	v_lshlrev_b32_e32 v149, 16, v14
	v_and_b32_e32 v150, 0xffff0000, v14
	v_lshlrev_b32_e32 v151, 16, v15
	v_and_b32_e32 v156, 0xffff0000, v15
	v_fmac_f32_e32 v146, v137, v136
	v_fmac_f32_e32 v147, v137, v138
	v_fmac_f32_e32 v140, v137, v139
	v_fmac_f32_e32 v141, v137, v148
	v_fmac_f32_e32 v142, v137, v149
	v_fmac_f32_e32 v143, v137, v150
	v_fmac_f32_e32 v144, v137, v151
	v_fmac_f32_e32 v145, v137, v156
	ds_read2_b32 v[136:137], v155 offset0:32 offset1:48
	v_lshlrev_b32_e32 v138, 16, v20
	v_and_b32_e32 v139, 0xffff0000, v20
	v_lshlrev_b32_e32 v148, 16, v21
	v_and_b32_e32 v149, 0xffff0000, v21
	v_lshlrev_b32_e32 v150, 16, v22
	v_and_b32_e32 v151, 0xffff0000, v22
	v_lshlrev_b32_e32 v156, 16, v23
	v_and_b32_e32 v157, 0xffff0000, v23
	s_waitcnt lgkmcnt(0)
	v_fmac_f32_e32 v146, v136, v138
	v_fmac_f32_e32 v147, v136, v139
	v_fmac_f32_e32 v140, v136, v148
	v_fmac_f32_e32 v141, v136, v149
	v_fmac_f32_e32 v142, v136, v150
	v_fmac_f32_e32 v143, v136, v151
	v_fmac_f32_e32 v144, v136, v156
	v_fmac_f32_e32 v145, v136, v157
	v_lshlrev_b32_e32 v136, 16, v28
	v_and_b32_e32 v138, 0xffff0000, v28
	v_lshlrev_b32_e32 v139, 16, v29
	v_and_b32_e32 v148, 0xffff0000, v29
	v_lshlrev_b32_e32 v149, 16, v30
	v_and_b32_e32 v150, 0xffff0000, v30
	v_lshlrev_b32_e32 v151, 16, v31
	v_and_b32_e32 v156, 0xffff0000, v31
	v_fmac_f32_e32 v146, v137, v136
	v_fmac_f32_e32 v147, v137, v138
	v_fmac_f32_e32 v140, v137, v139
	v_fmac_f32_e32 v141, v137, v148
	v_fmac_f32_e32 v142, v137, v149
	v_fmac_f32_e32 v143, v137, v150
	v_fmac_f32_e32 v144, v137, v151
	v_fmac_f32_e32 v145, v137, v156
	ds_read2_b32 v[136:137], v155 offset0:64 offset1:80
	v_lshlrev_b32_e32 v138, 16, v36
	v_and_b32_e32 v139, 0xffff0000, v36
	v_lshlrev_b32_e32 v148, 16, v37
	v_and_b32_e32 v149, 0xffff0000, v37
	v_lshlrev_b32_e32 v150, 16, v38
	v_and_b32_e32 v151, 0xffff0000, v38
	v_lshlrev_b32_e32 v156, 16, v39
	v_and_b32_e32 v157, 0xffff0000, v39
	s_waitcnt lgkmcnt(0)
; __device__ __forceinline__ void dsa_tile(const Params& p, unsigned char* smem, int tile) {
;     ...
;             for (int h = 0; h < 16; ++h) { const float wh = wl[h * 16 + fr]; float f[8]; unpack8(yf[h][ks], f);
; #pragma unroll
;                 for (int e = 0; e < 8; ++e) c[e] += wh * f[e]; }
	v_fmac_f32_e32 v146, v136, v138
	v_fmac_f32_e32 v147, v136, v139
	v_fmac_f32_e32 v140, v136, v148
	v_fmac_f32_e32 v141, v136, v149
	v_fmac_f32_e32 v142, v136, v150
	v_fmac_f32_e32 v143, v136, v151
	v_fmac_f32_e32 v144, v136, v156
	v_fmac_f32_e32 v145, v136, v157
	v_lshlrev_b32_e32 v136, 16, v44
	v_and_b32_e32 v138, 0xffff0000, v44
	v_lshlrev_b32_e32 v139, 16, v45
	v_and_b32_e32 v148, 0xffff0000, v45
	v_lshlrev_b32_e32 v149, 16, v46
	v_and_b32_e32 v150, 0xffff0000, v46
	v_lshlrev_b32_e32 v151, 16, v47
	v_and_b32_e32 v156, 0xffff0000, v47
	v_fmac_f32_e32 v146, v137, v136
	v_fmac_f32_e32 v147, v137, v138
	v_fmac_f32_e32 v140, v137, v139
	v_fmac_f32_e32 v141, v137, v148
	v_fmac_f32_e32 v142, v137, v149
	v_fmac_f32_e32 v143, v137, v150
	v_fmac_f32_e32 v144, v137, v151
	v_fmac_f32_e32 v145, v137, v156
	ds_read2_b32 v[136:137], v155 offset0:96 offset1:112
	v_lshlrev_b32_e32 v138, 16, v52
	v_and_b32_e32 v139, 0xffff0000, v52
	v_lshlrev_b32_e32 v148, 16, v53
	v_and_b32_e32 v149, 0xffff0000, v53
	v_lshlrev_b32_e32 v150, 16, v54
	v_and_b32_e32 v151, 0xffff0000, v54
	v_lshlrev_b32_e32 v156, 16, v55
	v_and_b32_e32 v157, 0xffff0000, v55
	s_waitcnt lgkmcnt(0)
	v_fmac_f32_e32 v146, v136, v138
	v_fmac_f32_e32 v147, v136, v139
	v_fmac_f32_e32 v140, v136, v148
	v_fmac_f32_e32 v141, v136, v149
	v_fmac_f32_e32 v142, v136, v150
	v_fmac_f32_e32 v143, v136, v151
	v_fmac_f32_e32 v144, v136, v156
	v_fmac_f32_e32 v145, v136, v157
	v_lshlrev_b32_e32 v136, 16, v60
	v_and_b32_e32 v138, 0xffff0000, v60
	v_lshlrev_b32_e32 v139, 16, v61
	v_and_b32_e32 v148, 0xffff0000, v61
	v_lshlrev_b32_e32 v149, 16, v62
	v_and_b32_e32 v150, 0xffff0000, v62
	v_lshlrev_b32_e32 v151, 16, v63
	v_and_b32_e32 v156, 0xffff0000, v63
	v_fmac_f32_e32 v146, v137, v136
	v_fmac_f32_e32 v147, v137, v138
	v_fmac_f32_e32 v140, v137, v139
	v_fmac_f32_e32 v141, v137, v148
	v_fmac_f32_e32 v142, v137, v149
	v_fmac_f32_e32 v143, v137, v150
	v_fmac_f32_e32 v144, v137, v151
	v_fmac_f32_e32 v145, v137, v156
	ds_read2_b32 v[136:137], v155 offset0:128 offset1:144
	v_lshlrev_b32_e32 v138, 16, v68
	v_and_b32_e32 v139, 0xffff0000, v68
	v_lshlrev_b32_e32 v148, 16, v69
	v_and_b32_e32 v149, 0xffff0000, v69
	v_lshlrev_b32_e32 v150, 16, v70
	v_and_b32_e32 v151, 0xffff0000, v70
	v_lshlrev_b32_e32 v156, 16, v71
	v_and_b32_e32 v157, 0xffff0000, v71
	s_waitcnt lgkmcnt(0)
	v_fmac_f32_e32 v146, v136, v138
	v_fmac_f32_e32 v147, v136, v139
	v_fmac_f32_e32 v140, v136, v148
	v_fmac_f32_e32 v141, v136, v149
	v_fmac_f32_e32 v142, v136, v150
	v_fmac_f32_e32 v143, v136, v151
	v_fmac_f32_e32 v144, v136, v156
	v_fmac_f32_e32 v145, v136, v157
	v_lshlrev_b32_e32 v136, 16, v76
	v_and_b32_e32 v138, 0xffff0000, v76
	v_lshlrev_b32_e32 v139, 16, v77
	v_and_b32_e32 v148, 0xffff0000, v77
	v_lshlrev_b32_e32 v149, 16, v78
	v_and_b32_e32 v150, 0xffff0000, v78
	v_lshlrev_b32_e32 v151, 16, v79
	v_and_b32_e32 v156, 0xffff0000, v79
	v_fmac_f32_e32 v146, v137, v136
	v_fmac_f32_e32 v147, v137, v138
	v_fmac_f32_e32 v140, v137, v139
	v_fmac_f32_e32 v141, v137, v148
	v_fmac_f32_e32 v142, v137, v149
	v_fmac_f32_e32 v143, v137, v150
	v_fmac_f32_e32 v144, v137, v151
	v_fmac_f32_e32 v145, v137, v156
	ds_read2_b32 v[136:137], v155 offset0:160 offset1:176
	v_lshlrev_b32_e32 v138, 16, v84
	v_and_b32_e32 v139, 0xffff0000, v84
	v_lshlrev_b32_e32 v148, 16, v85
	v_and_b32_e32 v149, 0xffff0000, v85
	v_lshlrev_b32_e32 v150, 16, v86
	v_and_b32_e32 v151, 0xffff0000, v86
	v_lshlrev_b32_e32 v156, 16, v87
	v_and_b32_e32 v157, 0xffff0000, v87
	s_waitcnt lgkmcnt(0)
	v_fmac_f32_e32 v146, v136, v138
	v_fmac_f32_e32 v147, v136, v139
	v_fmac_f32_e32 v140, v136, v148
	v_fmac_f32_e32 v141, v136, v149
	v_fmac_f32_e32 v142, v136, v150
	v_fmac_f32_e32 v143, v136, v151
	v_fmac_f32_e32 v144, v136, v156
	v_fmac_f32_e32 v145, v136, v157
	v_lshlrev_b32_e32 v136, 16, v92
	v_and_b32_e32 v138, 0xffff0000, v92
	v_lshlrev_b32_e32 v139, 16, v93
	v_and_b32_e32 v148, 0xffff0000, v93
	v_lshlrev_b32_e32 v149, 16, v94
	v_and_b32_e32 v150, 0xffff0000, v94
	v_lshlrev_b32_e32 v151, 16, v95
	v_and_b32_e32 v156, 0xffff0000, v95
	v_fmac_f32_e32 v146, v137, v136
	v_fmac_f32_e32 v147, v137, v138
	v_fmac_f32_e32 v140, v137, v139
	v_fmac_f32_e32 v141, v137, v148
	v_fmac_f32_e32 v142, v137, v149
	v_fmac_f32_e32 v143, v137, v150
	v_fmac_f32_e32 v144, v137, v151
	v_fmac_f32_e32 v145, v137, v156
	ds_read2_b32 v[136:137], v155 offset0:192 offset1:208
	v_lshlrev_b32_e32 v138, 16, v100
	v_and_b32_e32 v139, 0xffff0000, v100
	v_lshlrev_b32_e32 v148, 16, v101
	v_and_b32_e32 v149, 0xffff0000, v101
	v_lshlrev_b32_e32 v150, 16, v102
	v_and_b32_e32 v151, 0xffff0000, v102
	v_lshlrev_b32_e32 v156, 16, v103
	v_and_b32_e32 v157, 0xffff0000, v103
	s_waitcnt lgkmcnt(0)
; __device__ __forceinline__ void dsa_tile(const Params& p, unsigned char* smem, int tile) {
;     ...
;             chi[ks] = pack8(c);
;             float fh[8]; unpack8(chi[ks], fh);
; #pragma unroll
;             for (int e = 0; e < 8; ++e) c[e] -= fh[e];
;             clo[ks] = pack8(c);
;         }
;         float wv[16];
; #pragma unroll
;         for (int h = 0; h < 16; ++h) wv[h] = wl[h * 16 + fr];
;         const int nkb = qt + 1;
;         const bf16_t* kbase = (const bf16_t*)(p.ws + WS_IKC) + (size_t)b * SEQ * 64 + lane * 8;
;         int kb = wid;
;         u32x4 x0 = {0u, 0u, 0u, 0u}, x1 = x0;
;         if (kb < nkb) { const bf16_t* kr = kbase + (size_t)kb * 16 * 64; x0 = *(const u32x4*)kr; x1 = *(const u32x4*)(kr + 512); }
;         for (; kb < nkb; kb += 8) {
;             const int kn = (kb + 8 < nkb) ? kb + 8 : kb;
;             const bf16_t* kr = kbase + (size_t)kn * 16 * 64;
;             const u32x4 nx0 = *(const u32x4*)kr, nx1 = *(const u32x4*)(kr + 512);
	v_fmac_f32_e32 v146, v136, v138
	v_fmac_f32_e32 v147, v136, v139
	v_fmac_f32_e32 v140, v136, v148
	v_fmac_f32_e32 v141, v136, v149
	v_fmac_f32_e32 v142, v136, v150
	v_fmac_f32_e32 v143, v136, v151
	v_fmac_f32_e32 v144, v136, v156
	v_fmac_f32_e32 v145, v136, v157
	v_lshlrev_b32_e32 v136, 16, v108
	v_and_b32_e32 v138, 0xffff0000, v108
	v_lshlrev_b32_e32 v139, 16, v109
	v_and_b32_e32 v148, 0xffff0000, v109
	v_lshlrev_b32_e32 v149, 16, v110
	v_and_b32_e32 v150, 0xffff0000, v110
	v_lshlrev_b32_e32 v151, 16, v111
	v_and_b32_e32 v156, 0xffff0000, v111
	v_fmac_f32_e32 v146, v137, v136
	v_fmac_f32_e32 v147, v137, v138
	v_fmac_f32_e32 v140, v137, v139
	v_fmac_f32_e32 v141, v137, v148
	v_fmac_f32_e32 v142, v137, v149
	v_fmac_f32_e32 v143, v137, v150
	v_fmac_f32_e32 v144, v137, v151
	v_fmac_f32_e32 v145, v137, v156
	ds_read2_b32 v[136:137], v155 offset0:224 offset1:240
	v_lshlrev_b32_e32 v138, 16, v116
	v_and_b32_e32 v139, 0xffff0000, v116
	v_lshlrev_b32_e32 v148, 16, v117
	v_and_b32_e32 v149, 0xffff0000, v117
	v_lshlrev_b32_e32 v150, 16, v118
	v_and_b32_e32 v151, 0xffff0000, v118
	v_lshlrev_b32_e32 v156, 16, v119
	v_and_b32_e32 v157, 0xffff0000, v119
	s_waitcnt lgkmcnt(0)
	v_fmac_f32_e32 v146, v136, v138
	v_fmac_f32_e32 v147, v136, v139
	v_fmac_f32_e32 v140, v136, v148
	v_fmac_f32_e32 v141, v136, v149
	v_fmac_f32_e32 v142, v136, v150
	v_fmac_f32_e32 v143, v136, v151
	v_fmac_f32_e32 v144, v136, v156
	v_fmac_f32_e32 v145, v136, v157
	v_lshlrev_b32_e32 v136, 16, v124
	v_and_b32_e32 v138, 0xffff0000, v124
	v_lshlrev_b32_e32 v139, 16, v125
	v_and_b32_e32 v148, 0xffff0000, v125
	v_lshlrev_b32_e32 v149, 16, v126
	v_and_b32_e32 v150, 0xffff0000, v126
	v_lshlrev_b32_e32 v151, 16, v127
	v_and_b32_e32 v156, 0xffff0000, v127
	s_ashr_i32 s10, s15, 6
	v_fmac_f32_e32 v146, v137, v136
	v_fmac_f32_e32 v147, v137, v138
	v_fmac_f32_e32 v140, v137, v139
	v_fmac_f32_e32 v141, v137, v148
	v_fmac_f32_e32 v142, v137, v149
	v_fmac_f32_e32 v143, v137, v150
	v_fmac_f32_e32 v144, v137, v151
	v_fmac_f32_e32 v145, v137, v156
	v_cvt_pk_bf16_f32 v136, v146, v147
	v_cvt_pk_bf16_f32 v137, v140, v141
	v_cvt_pk_bf16_f32 v138, v142, v143
	v_cvt_pk_bf16_f32 v139, v144, v145
	s_cmp_gt_i32 s10, s14
	v_and_b32_e32 v151, 0xffff0000, v137
	v_lshlrev_b32_e32 v156, 16, v138
	v_and_b32_e32 v157, 0xffff0000, v138
	v_lshlrev_b32_e32 v148, 16, v136
	v_and_b32_e32 v149, 0xffff0000, v136
	v_lshlrev_b32_e32 v150, 16, v137
	v_lshlrev_b32_e32 v158, 16, v139
	v_and_b32_e32 v159, 0xffff0000, v139
	v_sub_f32_e32 v141, v141, v151
	v_sub_f32_e32 v142, v142, v156
	v_sub_f32_e32 v143, v143, v157
	v_sub_f32_e32 v146, v146, v148
	v_sub_f32_e32 v147, v147, v149
	v_sub_f32_e32 v148, v140, v150
	v_sub_f32_e32 v144, v144, v158
	v_sub_f32_e32 v145, v145, v159
	v_cvt_pk_bf16_f32 v140, v146, v147
	v_cvt_pk_bf16_f32 v141, v148, v141
	v_cvt_pk_bf16_f32 v142, v142, v143
	v_cvt_pk_bf16_f32 v143, v144, v145
	s_cbranch_scc1 .LBB0_290
	s_lshl_b64 s[4:5], s[8:9], 20
	v_and_b32_e32 v144, 63, v152
	s_add_u32 s4, s88, s4
	s_addc_u32 s5, s89, s5
	v_lshlrev_b32_e32 v160, 4, v144
	s_ashr_i32 s11, s10, 31
	v_lshl_add_u64 v[162:163], s[4:5], 0, v[160:161]
	s_lshl_b64 s[4:5], s[10:11], 11
	v_lshl_add_u64 v[144:145], v[162:163], 0, s[4:5]
	global_load_dwordx4 v[148:151], v[144:145], off
	s_nop 0
	global_load_dwordx4 v[144:147], v[144:145], off offset:1024
	v_add_u32_e32 v186, 0xa200, v154
	v_add_u32_e32 v187, 0xa240, v154
	v_add_u32_e32 v188, 0xa280, v154
	v_add_u32_e32 v189, 0xa2c0, v154
	v_add_u32_e32 v190, 0xa300, v154
	v_add_u32_e32 v191, 0xa340, v154
	v_add_u32_e32 v192, 0xa380, v154
	v_add_u32_e32 v156, 0xa040, v154
	v_add_u32_e32 v157, 0xa080, v154
	v_add_u32_e32 v158, 0xa0c0, v154
	v_add_u32_e32 v159, 0xa100, v154
	v_add_u32_e32 v160, 0xa140, v154
	v_add_u32_e32 v164, 0xa180, v154
	v_add_u32_e32 v165, 0xa1c0, v154
	v_add_u32_e32 v154, 0xa3c0, v154
	ds_read_b32 v178, v155
	ds_read_b32 v179, v156
	ds_read_b32 v180, v157
	ds_read_b32 v181, v158
	ds_read_b32 v182, v159
	ds_read_b32 v183, v160
	ds_read_b32 v184, v164
	ds_read_b32 v185, v165
	ds_read_b32 v186, v186
	ds_read_b32 v187, v187
	ds_read_b32 v188, v188
	ds_read_b32 v189, v189
	ds_read_b32 v190, v190
	ds_read_b32 v191, v191
	ds_read_b32 v192, v192
	ds_read_b32 v193, v154
	s_lshl_b32 s4, s10, 4
	s_ashr_i32 s5, s4, 31
	s_lshl_b64 s[4:5], s[4:5], 2
	v_and_b32_e32 v152, 48, v152
	s_add_u32 s4, s92, s4
	v_lshl_or_b32 v160, v153, 15, v152
	s_addc_u32 s5, s93, s5
	v_lshl_add_u64 v[164:165], s[4:5], 0, v[160:161]
	s_mov_b32 s12, s10
	s_cmp_lt_u32 s10, 4
	s_cbranch_scc1 .Lidx_noprio
	s_setprio 1
	s_sleep 5
